# bit-exact instruction trims: GLA scan (packed state scale, packed causal masks, 4-instruction chunk row lookup) and qk-norm sign fold
# baseline (speedup 1.0000x reference)
; __device__ __forceinline__ void gla_scan_phase(const Params& p, int j, bool need_ctx, char* smem, int tid, int bid) {
;     ...
;   for (int unit = bid; unit < 256; unit += gridDim.x) {
;     int dir, dvs, h, b;
;     if (gridDim.x == 256) { const int g = (unit & 7) * 8 + (unit >> 5); dvs = (unit >> 3) & 3; dir = g & 1; h = (g >> 1) & 3; b = g >> 3; }
;     else { dir = unit & 1; dvs = (unit >> 1) & 3; h = (unit >> 3) & 3; b = unit >> 5; }
;     const int dvc = tid & 63, tg = tid >> 6;
;     f32x16 Sacc;
; #pragma unroll
;     for (int r = 0; r < 16; ++r) Sacc[r] = 0.f;
;     __syncthreads();
;     { u32x4 z = {0u, 0u, 0u, 0u}; *(u32x4*)(STL + tid * 32) = z; *(u32x4*)(STL + tid * 32 + 16) = z; }
;     u32x4 qx[2], kx[2]; unsigned kt[16], vv[8]; float ebv = 0.f;
;     const u16* QB = (const u16*)(p.ws + OFF_GQB);
;     const u16* KB2 = (const u16*)((const char*)p.out + OUT_GKB);
;     const float* EBE = (const float*)((const char*)p.out + OUT_EBE);
;     const u16* qsrc = dir ? QB + h * 128 : P + h * 128;
;     const u16* ksrc = dir ? KB2 + h * 128 : P + 512 + h * 128;
;     const long rst = dir ? 512 : LDP;
;     const long sgn = dir ? -1 : 1;
;     ...
;     GLA_PREFETCH(0);
;     ...
;           const int t = tb * 32 + l32;
; #pragma unroll
;           for (int rg = 0; rg < 4; ++rg) {
;             const int s0 = sb * 32 + 8 * rg + 4 * hi;
;             const float v0 = (s0 + 0 <= t) ? sacc[rg * 4 + 0] : 0.f, v1 = (s0 + 1 <= t) ? sacc[rg * 4 + 1] : 0.f;
;             const float v2 = (s0 + 2 <= t) ? sacc[rg * 4 + 2] : 0.f, v3 = (s0 + 3 <= t) ? sacc[rg * 4 + 3] : 0.f;
;             u32x2 w = {cvtpk(v0, v1), cvtpk(v2, v3)};
;             *(u32x2*)(scL + swz128(t, s0 >> 3) + (s0 & 7) * 2) = w;
;           }
.Lgs_masks:
	s_lshl_b32 s9, s4, 5
	v_lshl_add_u32 v109, v103, 2, s9
	s_lshl_b32 s9, s77, 5
	v_add_u32_e32 v108, s9, v102
	v_mov_b32_e32 v200, 0xffff
	v_add_u32_e32 v198, 0, v109
	v_cmp_le_u32_e32 vcc, v198, v108
	s_nop 1
	v_cndmask_b32_e32 v204, 0, v200, vcc
	v_add_u32_e32 v198, 1, v109
	v_cmp_le_u32_e32 vcc, v198, v108
	s_nop 1
	v_cndmask_b32_e32 v199, 0, v200, vcc
	v_lshl_or_b32 v204, v199, 16, v204
	v_add_u32_e32 v198, 2, v109
	v_cmp_le_u32_e32 vcc, v198, v108
	s_nop 1
	v_cndmask_b32_e32 v205, 0, v200, vcc
	v_add_u32_e32 v198, 3, v109
	v_cmp_le_u32_e32 vcc, v198, v108
	s_nop 1
	v_cndmask_b32_e32 v199, 0, v200, vcc
	v_lshl_or_b32 v205, v199, 16, v205
	v_add_u32_e32 v198, 8, v109
	v_cmp_le_u32_e32 vcc, v198, v108
	s_nop 1
	v_cndmask_b32_e32 v206, 0, v200, vcc
	v_add_u32_e32 v198, 9, v109
	v_cmp_le_u32_e32 vcc, v198, v108
	s_nop 1
	v_cndmask_b32_e32 v199, 0, v200, vcc
	v_lshl_or_b32 v206, v199, 16, v206
	v_add_u32_e32 v198, 10, v109
	v_cmp_le_u32_e32 vcc, v198, v108
	s_nop 1
	v_cndmask_b32_e32 v207, 0, v200, vcc
	v_add_u32_e32 v198, 11, v109
	v_cmp_le_u32_e32 vcc, v198, v108
	s_nop 1
	v_cndmask_b32_e32 v199, 0, v200, vcc
	v_lshl_or_b32 v207, v199, 16, v207
	v_add_u32_e32 v198, 16, v109
	v_cmp_le_u32_e32 vcc, v198, v108
	s_nop 1
	v_cndmask_b32_e32 v208, 0, v200, vcc
	v_add_u32_e32 v198, 17, v109
	v_cmp_le_u32_e32 vcc, v198, v108
	s_nop 1
	v_cndmask_b32_e32 v199, 0, v200, vcc
	v_lshl_or_b32 v208, v199, 16, v208
	v_add_u32_e32 v198, 18, v109
	v_cmp_le_u32_e32 vcc, v198, v108
	s_nop 1
	v_cndmask_b32_e32 v209, 0, v200, vcc
	v_add_u32_e32 v198, 19, v109
	v_cmp_le_u32_e32 vcc, v198, v108
	s_nop 1
	v_cndmask_b32_e32 v199, 0, v200, vcc
	v_lshl_or_b32 v209, v199, 16, v209
	v_add_u32_e32 v198, 24, v109
	v_cmp_le_u32_e32 vcc, v198, v108
	s_nop 1
	v_cndmask_b32_e32 v210, 0, v200, vcc
	v_add_u32_e32 v198, 25, v109
	v_cmp_le_u32_e32 vcc, v198, v108
	s_nop 1
	v_cndmask_b32_e32 v199, 0, v200, vcc
	v_lshl_or_b32 v210, v199, 16, v210
	v_add_u32_e32 v198, 26, v109
	v_cmp_le_u32_e32 vcc, v198, v108
	s_nop 1
	v_cndmask_b32_e32 v211, 0, v200, vcc
	v_add_u32_e32 v198, 27, v109
	v_cmp_le_u32_e32 vcc, v198, v108
	s_nop 1
	v_cndmask_b32_e32 v199, 0, v200, vcc
	v_lshl_or_b32 v211, v199, 16, v211
.Lgs_roles_done:
	s_lshl_b32 s0, s35, 8
	s_add_u32 s0, s0, 0x8000
	s_lshl_b32 s1, s35, 12
	s_cmp_eq_u32 s55, 0
	s_cselect_b32 s4, 64, -64
	s_cselect_b32 s5, 0, 0xc0
	s_cselect_b32 s8, 0, 0xfc0
	s_add_u32 s35, s0, s5
	s_add_u32 s1, s1, s8
	s_lshl_b32 s5, s4, 2
	s_sub_u32 s55, s1, s5
	s_mov_b32 s80, s4
	s_waitcnt vmcnt(0) lgkmcnt(0)
	s_barrier
	v_lshlrev_b32_e32 v198, 5, v203
	v_add_u32_e32 v198, 98304, v198
	v_mov_b32_e32 v112, 0
	v_mov_b32_e32 v113, 0
	v_mov_b32_e32 v114, 0
	v_mov_b32_e32 v115, 0
	ds_write_b128 v198, v[112:115]
	ds_write_b128 v198, v[112:115] offset:16
	v_mov_b32_e32 v0, 0
	v_mov_b32_e32 v1, 0
	v_mov_b32_e32 v2, 0
	v_mov_b32_e32 v3, 0
	v_mov_b32_e32 v4, 0
	v_mov_b32_e32 v5, 0
	v_mov_b32_e32 v6, 0
	v_mov_b32_e32 v7, 0
	v_mov_b32_e32 v8, 0
	v_mov_b32_e32 v9, 0
	v_mov_b32_e32 v10, 0
	v_mov_b32_e32 v11, 0
	v_mov_b32_e32 v12, 0
	v_mov_b32_e32 v13, 0
	v_mov_b32_e32 v14, 0
	v_mov_b32_e32 v15, 0
	s_mov_b32 s54, 0
	s_cmp_lt_u32 s54, 4
	s_cselect_b32 s0, s35, s55
	s_mul_i32 s1, s54, s80
	s_add_u32 s0, s0, s1
	s_mul_i32 s1, s0, s34
	s_add_u32 s6, s22, s1
	s_addc_u32 s7, s23, 0
	s_add_u32 s8, s24, s1
	s_addc_u32 s9, s25, 0
	s_mul_i32 s1, s0, 0x1840
	s_add_u32 s10, s26, s1
	s_addc_u32 s11, s27, 0
	s_lshr_b32 s1, s0, 6
	s_lshl_b32 s1, s1, 11
	s_add_u32 s18, s28, s1
	s_addc_u32 s19, s29, 0
	global_load_dwordx4 v[112:115], v134, s[6:7]
	global_load_dwordx4 v[116:119], v134, s[6:7] offset:128
	global_load_dwordx4 v[120:123], v134, s[8:9]
	global_load_dwordx4 v[124:127], v134, s[8:9] offset:128
	global_load_dwordx4 v[128:131], v135, s[10:11]
	global_load_dword v132, v145, s[18:19]
	s_mov_b32 s65, 1
	s_cmp_lt_u32 s65, 4
	s_cselect_b32 s0, s35, s55
	s_mul_i32 s1, s65, s80
	s_add_u32 s0, s0, s1
	s_mul_i32 s1, s0, s34
	s_add_u32 s6, s22, s1
	s_addc_u32 s7, s23, 0
	s_add_u32 s8, s24, s1
	s_addc_u32 s9, s25, 0
	s_mul_i32 s1, s0, 0x1840
	s_add_u32 s10, s26, s1
	s_addc_u32 s11, s27, 0
	s_lshr_b32 s1, s0, 6
	s_lshl_b32 s1, s1, 11
	s_add_u32 s18, s28, s1
	s_addc_u32 s19, s29, 0
	global_load_dwordx4 v[96:99], v134, s[6:7]
	global_load_dwordx4 v[100:103], v134, s[6:7] offset:128
	global_load_dwordx4 v[104:107], v134, s[8:9]
	global_load_dwordx4 v[108:111], v134, s[8:9] offset:128
	global_load_dwordx4 v[136:139], v135, s[10:11]
	global_load_dword v133, v145, s[18:19]
	s_mov_b32 s65, 2
	s_cmp_lt_u32 s65, 4
	s_cselect_b32 s0, s35, s55
	s_mul_i32 s1, s65, s80
	s_add_u32 s0, s0, s1
	s_mul_i32 s1, s0, s34
	s_add_u32 s6, s22, s1
	s_addc_u32 s7, s23, 0
	s_add_u32 s8, s24, s1
	s_addc_u32 s9, s25, 0
	s_mul_i32 s1, s0, 0x1840
	s_add_u32 s10, s26, s1
	s_addc_u32 s11, s27, 0
	s_lshr_b32 s1, s0, 6
	s_lshl_b32 s1, s1, 11
	s_add_u32 s18, s28, s1
	s_addc_u32 s19, s29, 0
	global_load_dwordx4 v[222:225], v134, s[6:7]
	global_load_dwordx4 v[226:229], v134, s[6:7] offset:128
	global_load_dwordx4 v[230:233], v134, s[8:9]
	global_load_dwordx4 v[234:237], v134, s[8:9] offset:128
	global_load_dwordx4 v[244:247], v135, s[10:11]
	global_load_dword v248, v145, s[18:19]
	s_mov_b32 s97, 0
	s_mov_b32 s72, 0
	s_mov_b32 s16, 0
	s_waitcnt vmcnt(12)
	ds_write_b128 v194, v[112:115] offset:0
	ds_write_b128 v195, v[116:119] offset:0
	ds_write_b128 v143, v[120:123] offset:16384
	ds_write_b128 v144, v[124:127] offset:16384
	ds_write_b128 v196, v[128:131] offset:0
	s_cmp_gt_u32 s81, 1
	s_cbranch_scc1 .Lgs_noeb_pro
	ds_write_b32 v197, v132 offset:0
; __device__ __forceinline__ void gla_scan_phase(const Params& p, int j, bool need_ctx, char* smem, int tid, int bid) {
;     ...
;       } else if (wid < 4) {
;         const int sb = wid & 1, tb = wid >> 1;
;         if (sb <= tb) {
;           f32x16 sacc;
; #pragma unroll
;           for (int r = 0; r < 16; ++r) sacc[r] = 0.f;
;           bf16x8 av[8], bv8[8];
; #pragma unroll
;           for (int k16 = 0; k16 < 8; ++k16) {
;             av[k16] = *(const bf16x8*)(kinvL + swz256(sb * 32 + l32, k16 * 2 + hi));
;             bv8[k16] = *(const bf16x8*)(qbL + swz256(tb * 32 + l32, k16 * 2 + hi));
;           }
; #pragma unroll
;           for (int k16 = 0; k16 < 8; ++k16) sacc = __builtin_amdgcn_mfma_f32_32x32x16_bf16(av[k16], bv8[k16], sacc, 0, 0, 0);
;           const int t = tb * 32 + l32;
; #pragma unroll
;           for (int rg = 0; rg < 4; ++rg) {
;             const int s0 = sb * 32 + 8 * rg + 4 * hi;
;             const float v0 = (s0 + 0 <= t) ? sacc[rg * 4 + 0] : 0.f, v1 = (s0 + 1 <= t) ? sacc[rg * 4 + 1] : 0.f;
;             const float v2 = (s0 + 2 <= t) ? sacc[rg * 4 + 2] : 0.f, v3 = (s0 + 3 <= t) ? sacc[rg * 4 + 3] : 0.f;
;             u32x2 w = {cvtpk(v0, v1), cvtpk(v2, v3)};
;             *(u32x2*)(scL + swz128(t, s0 >> 3) + (s0 & 7) * 2) = w;
;           }
;         }
;       } else {
;         bf16x8 av[8], bv8[8];
; #pragma unroll
;         for (int k16 = 0; k16 < 8; ++k16) {
;           av[k16] = *(const bf16x8*)(qbL + swz256(tbo * 32 + l32, k16 * 2 + hi));
;           bv8[k16] = *(const bf16x8*)(STL + swz256(dvbo * 32 + l32, k16 * 2 + hi));
;         }
; #pragma unroll
;         for (int k16 = 0; k16 < 8; ++k16) oacc = __builtin_amdgcn_mfma_f32_32x32x16_bf16(av[k16], bv8[k16], oacc, 0, 0, 0);
;       }
;       const int kb = wid >> 1, dvb2 = wid & 1;
;       {
;         bf16x8 av[4], bv4[4];
; #pragma unroll
;         for (int k16 = 0; k16 < 4; ++k16) {
;           av[k16] = *(const bf16x8*)(kendT + swz128(kb * 32 + l32, k16 * 2 + hi));
;           bv4[k16] = *(const bf16x8*)(vT + swz128(dvb2 * 32 + l32, k16 * 2 + hi));
;         }
; #pragma unroll
;         for (int k16 = 0; k16 < 4; ++k16) Sacc = __builtin_amdgcn_mfma_f32_32x32x16_bf16(av[k16], bv4[k16], Sacc, 0, 0, 0);
; #pragma unroll
;         for (int rg = 0; rg < 4; ++rg) {
;           const f32x4 e4 = *(const f32x4*)(ebend + kb * 32 + 8 * rg + 4 * hi);
.Lgs_noeb_pro:
.Lgs_pair:
.Lgs0_chunk:
	s_cmp_gt_u32 s54, 3
	s_cselect_b32 s96, 1, s60
	s_waitcnt lgkmcnt(0)
	s_barrier
	ds_read_b64_tr_b16 v[64:65], v140 offset:0
	ds_read_b64_tr_b16 v[66:67], v141 offset:0
	ds_read_b64_tr_b16 v[80:81], v142 offset:0
	ds_read_b64_tr_b16 v[82:83], v142 offset:512
	ds_read_b64_tr_b16 v[68:69], v140 offset:4096
	ds_read_b64_tr_b16 v[70:71], v141 offset:4096
	ds_read_b64_tr_b16 v[84:85], v142 offset:2048
	ds_read_b64_tr_b16 v[86:87], v142 offset:2560
	ds_read_b64_tr_b16 v[72:73], v140 offset:8192
	ds_read_b64_tr_b16 v[74:75], v141 offset:8192
	ds_read_b64_tr_b16 v[88:89], v142 offset:4096
	ds_read_b64_tr_b16 v[90:91], v142 offset:4608
	s_add_u32 s65, s54, 3
	s_min_u32 s65, s65, 67
	s_cmp_lt_u32 s65, 4
	s_cselect_b32 s0, s35, s55
	s_mul_i32 s1, s65, s80
	s_add_u32 s0, s0, s1
	s_mul_i32 s1, s0, s34
	s_add_u32 s6, s22, s1
	s_addc_u32 s7, s23, 0
	s_add_u32 s8, s24, s1
	s_addc_u32 s9, s25, 0
	s_mul_i32 s1, s0, 0x1840
	s_add_u32 s10, s26, s1
	s_addc_u32 s11, s27, 0
	s_lshr_b32 s1, s0, 6
	s_lshl_b32 s1, s1, 11
	s_add_u32 s18, s28, s1
	s_addc_u32 s19, s29, 0
	s_waitcnt lgkmcnt(8)
	v_mfma_f32_32x32x16_bf16 v[0:15], v[64:67], v[80:83], v[0:15]
	ds_read_b64_tr_b16 v[76:77], v140 offset:12288
	ds_read_b64_tr_b16 v[78:79], v141 offset:12288
	ds_read_b64_tr_b16 v[92:93], v142 offset:6144
	ds_read_b64_tr_b16 v[94:95], v142 offset:6656
	s_cmp_eq_u32 s96, 0
	s_cbranch_scc1 .Lgs0_nochain
	s_cmp_eq_u32 s76, 1
	s_cbranch_scc1 .Lgs0_nochain
	s_waitcnt lgkmcnt(8)
	v_mfma_f32_32x32x16_bf16 v[0:15], v[68:71], v[84:87], v[0:15]
	ds_read_b128 v[32:35], v243
	ds_read_b128 v[48:51], v221 offset:0
	v_xor_b32_e32 v198, 32, v243
	v_xor_b32_e32 v199, 32, v221
	ds_read_b128 v[36:39], v198
	ds_read_b128 v[52:55], v199 offset:0
	global_load_dwordx4 v[112:115], v134, s[6:7]
	s_waitcnt lgkmcnt(8)
	v_mfma_f32_32x32x16_bf16 v[0:15], v[72:75], v[88:91], v[0:15]
	v_xor_b32_e32 v198, 64, v243
	v_xor_b32_e32 v199, 64, v221
	ds_read_b128 v[40:43], v198
	ds_read_b128 v[56:59], v199 offset:0
	v_xor_b32_e32 v198, 96, v243
	v_xor_b32_e32 v199, 96, v221
	ds_read_b128 v[44:47], v198
	ds_read_b128 v[60:63], v199 offset:0
	global_load_dwordx4 v[116:119], v134, s[6:7] offset:128
	s_waitcnt lgkmcnt(8)
	v_mfma_f32_32x32x16_bf16 v[0:15], v[76:79], v[92:95], v[0:15]
	global_load_dwordx4 v[120:123], v134, s[8:9]
	s_waitcnt lgkmcnt(6)
	v_mfma_f32_32x32x16_bf16 v[16:31], v[32:35], v[48:51], 0
	v_xor_b32_e32 v198, 128, v243
	v_xor_b32_e32 v199, 128, v221
	ds_read_b128 v[32:35], v198
	ds_read_b128 v[48:51], v199 offset:0
	global_load_dwordx4 v[124:127], v134, s[8:9] offset:128
	s_waitcnt lgkmcnt(6)
	v_mfma_f32_32x32x16_bf16 v[16:31], v[36:39], v[52:55], v[16:31]
	v_xor_b32_e32 v198, 160, v243
	v_xor_b32_e32 v199, 160, v221
	ds_read_b128 v[36:39], v198
	ds_read_b128 v[52:55], v199 offset:0
	global_load_dwordx4 v[128:131], v135, s[10:11]
	s_waitcnt lgkmcnt(6)
	v_mfma_f32_32x32x16_bf16 v[16:31], v[40:43], v[56:59], v[16:31]
	v_xor_b32_e32 v198, 192, v243
	v_xor_b32_e32 v199, 192, v221
	ds_read_b128 v[40:43], v198
	ds_read_b128 v[56:59], v199 offset:0
	global_load_dword v132, v145, s[18:19]
	s_waitcnt lgkmcnt(6)
	v_mfma_f32_32x32x16_bf16 v[16:31], v[44:47], v[60:63], v[16:31]
	v_xor_b32_e32 v198, 224, v243
	v_xor_b32_e32 v199, 224, v221
	ds_read_b128 v[44:47], v198
	ds_read_b128 v[60:63], v199 offset:0
	s_waitcnt lgkmcnt(6)
	v_mfma_f32_32x32x16_bf16 v[16:31], v[32:35], v[48:51], v[16:31]
	ds_read_b128 v[178:181], v252 offset:0
	ds_read_b128 v[182:185], v252 offset:32
	ds_read_b128 v[186:189], v252 offset:64
	ds_read_b128 v[190:193], v252 offset:96
	s_waitcnt lgkmcnt(8)
	v_mfma_f32_32x32x16_bf16 v[16:31], v[36:39], v[52:55], v[16:31]
	s_waitcnt lgkmcnt(6)
	v_mfma_f32_32x32x16_bf16 v[16:31], v[40:43], v[56:59], v[16:31]
	s_waitcnt lgkmcnt(4)
	v_mfma_f32_32x32x16_bf16 v[16:31], v[44:47], v[60:63], v[16:31]
	s_cmp_eq_u32 s16, 0
	s_cbranch_scc1 .Lgs0_scale
	s_cmp_eq_u32 s76, 2
	s_cbranch_scc0 .Lgs0_scale
	v_xor_b32_e32 v198, 32, v249
	ds_read_b128 v[64:67], v249 offset:8192
	ds_read_b128 v[68:71], v198 offset:8192
	s_cmp_eq_u32 s77, 0
	s_cbranch_scc1 .Lgs0_ohalf
	v_xor_b32_e32 v199, 64, v249
	v_xor_b32_e32 v200, 96, v249
	ds_read_b128 v[72:75], v199 offset:8192
	ds_read_b128 v[76:79], v200 offset:8192
	s_waitcnt lgkmcnt(2)
	v_mfma_f32_32x32x16_bf16 v[146:161], v[162:165], v[64:67], v[146:161]
	v_mfma_f32_32x32x16_bf16 v[146:161], v[166:169], v[68:71], v[146:161]
	s_waitcnt lgkmcnt(0)
	v_mfma_f32_32x32x16_bf16 v[146:161], v[170:173], v[72:75], v[146:161]
	v_mfma_f32_32x32x16_bf16 v[146:161], v[174:177], v[76:79], v[146:161]
	s_branch .Lgs0_odone

; __device__ __forceinline__ void gla_scan_phase(const Params& p, int j, bool need_ctx, char* smem, int tid, int bid) {
;     ...
; #pragma unroll
;         for (int k16 = 0; k16 < 4; ++k16) Sacc = __builtin_amdgcn_mfma_f32_32x32x16_bf16(av[k16], bv4[k16], Sacc, 0, 0, 0);
; #pragma unroll
;         for (int rg = 0; rg < 4; ++rg) {
;           const f32x4 e4 = *(const f32x4*)(ebend + kb * 32 + 8 * rg + 4 * hi);
;           Sacc[rg * 4 + 0] *= e4[0]; Sacc[rg * 4 + 1] *= e4[1]; Sacc[rg * 4 + 2] *= e4[2]; Sacc[rg * 4 + 3] *= e4[3];
;         }
;     ...
;       {
;         const int dv = dvb2 * 32 + l32;
; #pragma unroll
;         for (int rg = 0; rg < 4; ++rg) {
;           const int k0 = kb * 32 + 8 * rg + 4 * hi;
;           u32x2 w = {cvtpk(Sacc[rg * 4 + 0], Sacc[rg * 4 + 1]), cvtpk(Sacc[rg * 4 + 2], Sacc[rg * 4 + 3])};
;           *(u32x2*)(STL + swz256(dv, k0 >> 3) + (k0 & 7) * 2) = w;
;         }
;       }
.Lgs0_scale:
	s_waitcnt lgkmcnt(0)
	v_pk_mul_f32 v[0:1], v[0:1], v[178:179]
	v_pk_mul_f32 v[2:3], v[2:3], v[180:181]
	v_pk_mul_f32 v[4:5], v[4:5], v[182:183]
	v_pk_mul_f32 v[6:7], v[6:7], v[184:185]
	v_pk_mul_f32 v[8:9], v[8:9], v[186:187]
	v_pk_mul_f32 v[10:11], v[10:11], v[188:189]
	v_pk_mul_f32 v[12:13], v[12:13], v[190:191]
	v_pk_mul_f32 v[14:15], v[14:15], v[192:193]
	v_cvt_pk_bf16_f32 v178, v0, v1
	v_cvt_pk_bf16_f32 v179, v2, v3
	v_cvt_pk_bf16_f32 v180, v4, v5
	v_cvt_pk_bf16_f32 v181, v6, v7
	v_cvt_pk_bf16_f32 v182, v8, v9
	v_cvt_pk_bf16_f32 v183, v10, v11
	v_cvt_pk_bf16_f32 v184, v12, v13
	v_cvt_pk_bf16_f32 v185, v14, v15
	v_xor_b32_e32 v198, 16, v250
	v_xor_b32_e32 v199, 32, v250
	v_xor_b32_e32 v200, 48, v250
	ds_write_b64 v250, v[178:179] offset:16384
	ds_write_b64 v198, v[180:181] offset:16384
	ds_write_b64 v199, v[182:183] offset:16384
	ds_write_b64 v200, v[184:185] offset:16384
	s_add_u32 s0, s97, s72
	s_cmp_eq_u32 s0, 4
	s_cbranch_scc1 .Lgs0_w16
	s_waitcnt vmcnt(12)
	s_branch .Lgs0_wd

; __device__ __forceinline__ u16 f2bf(float x) { return (u16)(cvtpk(x, 0.f) & 0xffffu); }
; __device__ __forceinline__ int crow(int r, int hi) { return (r & 3) + 8 * (r >> 2) + 4 * hi; }
; __device__ __forceinline__ void gla_scan_phase(const Params& p, int j, bool need_ctx, char* smem, int tid, int bid) {
;     ...
;           const int t = tb * 32 + l32;
; #pragma unroll
;           for (int rg = 0; rg < 4; ++rg) {
;             const int s0 = sb * 32 + 8 * rg + 4 * hi;
;             const float v0 = (s0 + 0 <= t) ? sacc[rg * 4 + 0] : 0.f, v1 = (s0 + 1 <= t) ? sacc[rg * 4 + 1] : 0.f;
;             const float v2 = (s0 + 2 <= t) ? sacc[rg * 4 + 2] : 0.f, v3 = (s0 + 3 <= t) ? sacc[rg * 4 + 3] : 0.f;
;             u32x2 w = {cvtpk(v0, v1), cvtpk(v2, v3)};
;             *(u32x2*)(scL + swz128(t, s0 >> 3) + (s0 & 7) * 2) = w;
;           }
;     ...
;         if (!is_ctx || need_ctx) {
;           u16* O = dir ? OB : OF;
; #pragma unroll
;           for (int r = 0; r < 16; ++r) {
;             const int pos = c * 64 + tbo * 32 + crow(r, hi);
;             const int tok = dir ? TT - 1 - pos : pos;
;             O[(size_t)(base + tok) * 1024 + h * 256 + dvs * 64 + dvbo * 32 + l32] = f2bf(oacc[r]);
;           }
;         }
.Lgs_noeb_b0:
	s_mov_b32 s72, s97
	s_mov_b32 s97, 0
	s_cmp_eq_u32 s76, 1
	s_cbranch_scc1 .Lgs0_next
	s_cmp_eq_u32 s76, 2
	s_cbranch_scc1 .Lgs0_otail
	s_cmp_eq_u32 s96, 0
	s_cbranch_scc1 .Lgs0_next
	v_cvt_pk_bf16_f32 v32, v16, v17
	v_cvt_pk_bf16_f32 v33, v18, v19
	v_cvt_pk_bf16_f32 v34, v20, v21
	v_cvt_pk_bf16_f32 v35, v22, v23
	v_cvt_pk_bf16_f32 v36, v24, v25
	v_cvt_pk_bf16_f32 v37, v26, v27
	v_cvt_pk_bf16_f32 v38, v28, v29
	v_cvt_pk_bf16_f32 v39, v30, v31
	v_and_b32_e32 v32, v204, v32
	v_and_b32_e32 v33, v205, v33
	v_and_b32_e32 v34, v206, v34
	v_and_b32_e32 v35, v207, v35
	v_and_b32_e32 v36, v208, v36
	v_and_b32_e32 v37, v209, v37
	v_and_b32_e32 v38, v210, v38
	v_and_b32_e32 v39, v211, v39
	v_xor_b32_e32 v198, 16, v249
	v_xor_b32_e32 v199, 32, v249
	v_xor_b32_e32 v200, 48, v249
	ds_write_b64 v249, v[32:33] offset:0
	ds_write_b64 v198, v[34:35] offset:0
	ds_write_b64 v199, v[36:37] offset:0
	ds_write_b64 v200, v[38:39] offset:0
	s_branch .Lgs0_next
.Lgs0_otail:
	s_cmp_eq_u32 s16, 0
	s_cbranch_scc1 .Lgs0_next
	s_add_i32 s65, s54, -1
	s_cmp_lt_u32 s65, 4
	s_cselect_b32 s0, s35, s55
	s_mul_i32 s1, s65, s80
	s_add_u32 s0, s0, s1
	s_lshl_b32 s1, s0, 11
	s_add_u32 s20, s30, s1
	s_addc_u32 s21, s31, 0
	v_cvt_pk_bf16_f32 v186, v146, v147
	v_cvt_pk_bf16_f32 v187, v148, v149
	v_cvt_pk_bf16_f32 v188, v150, v151
	v_cvt_pk_bf16_f32 v189, v152, v153
	v_cvt_pk_bf16_f32 v190, v154, v155
	v_cvt_pk_bf16_f32 v191, v156, v157
	v_cvt_pk_bf16_f32 v192, v158, v159
	v_cvt_pk_bf16_f32 v193, v160, v161
	s_nop 0
	v_permlane32_swap_b32_e32 v186, v188
	v_permlane32_swap_b32_e32 v187, v189
	v_permlane32_swap_b32_e32 v190, v192
	v_permlane32_swap_b32_e32 v191, v193
	global_store_dwordx4 v204, v[186:189], s[20:21]
	global_store_dwordx4 v204, v[190:193], s[20:21] offset:32
	s_mov_b32 s97, 2

; __device__ __forceinline__ void gla_scan_phase(const Params& p, int j, bool need_ctx, char* smem, int tid, int bid) {
;     ...
;       } else if (wid < 4) {
;         const int sb = wid & 1, tb = wid >> 1;
;         if (sb <= tb) {
;           f32x16 sacc;
; #pragma unroll
;           for (int r = 0; r < 16; ++r) sacc[r] = 0.f;
;           bf16x8 av[8], bv8[8];
; #pragma unroll
;           for (int k16 = 0; k16 < 8; ++k16) {
;             av[k16] = *(const bf16x8*)(kinvL + swz256(sb * 32 + l32, k16 * 2 + hi));
;             bv8[k16] = *(const bf16x8*)(qbL + swz256(tb * 32 + l32, k16 * 2 + hi));
;           }
; #pragma unroll
;           for (int k16 = 0; k16 < 8; ++k16) sacc = __builtin_amdgcn_mfma_f32_32x32x16_bf16(av[k16], bv8[k16], sacc, 0, 0, 0);
;           const int t = tb * 32 + l32;
; #pragma unroll
;           for (int rg = 0; rg < 4; ++rg) {
;             const int s0 = sb * 32 + 8 * rg + 4 * hi;
;             const float v0 = (s0 + 0 <= t) ? sacc[rg * 4 + 0] : 0.f, v1 = (s0 + 1 <= t) ? sacc[rg * 4 + 1] : 0.f;
;             const float v2 = (s0 + 2 <= t) ? sacc[rg * 4 + 2] : 0.f, v3 = (s0 + 3 <= t) ? sacc[rg * 4 + 3] : 0.f;
;             u32x2 w = {cvtpk(v0, v1), cvtpk(v2, v3)};
;             *(u32x2*)(scL + swz128(t, s0 >> 3) + (s0 & 7) * 2) = w;
;           }
;         }
;       } else {
;         bf16x8 av[8], bv8[8];
; #pragma unroll
;         for (int k16 = 0; k16 < 8; ++k16) {
;           av[k16] = *(const bf16x8*)(qbL + swz256(tbo * 32 + l32, k16 * 2 + hi));
;           bv8[k16] = *(const bf16x8*)(STL + swz256(dvbo * 32 + l32, k16 * 2 + hi));
;         }
; #pragma unroll
;         for (int k16 = 0; k16 < 8; ++k16) oacc = __builtin_amdgcn_mfma_f32_32x32x16_bf16(av[k16], bv8[k16], oacc, 0, 0, 0);
;       }
;       const int kb = wid >> 1, dvb2 = wid & 1;
;       {
;         bf16x8 av[4], bv4[4];
; #pragma unroll
;         for (int k16 = 0; k16 < 4; ++k16) {
;           av[k16] = *(const bf16x8*)(kendT + swz128(kb * 32 + l32, k16 * 2 + hi));
;           bv4[k16] = *(const bf16x8*)(vT + swz128(dvb2 * 32 + l32, k16 * 2 + hi));
;         }
; #pragma unroll
;         for (int k16 = 0; k16 < 4; ++k16) Sacc = __builtin_amdgcn_mfma_f32_32x32x16_bf16(av[k16], bv4[k16], Sacc, 0, 0, 0);
; #pragma unroll
;         for (int rg = 0; rg < 4; ++rg) {
;           const f32x4 e4 = *(const f32x4*)(ebend + kb * 32 + 8 * rg + 4 * hi);
.Lgs1_chunk:
	s_cmp_gt_u32 s54, 3
	s_cselect_b32 s96, 1, s60
	s_waitcnt lgkmcnt(0)
	s_barrier
	ds_read_b64_tr_b16 v[64:65], v140 offset:40960
	ds_read_b64_tr_b16 v[66:67], v141 offset:40960
	ds_read_b64_tr_b16 v[162:163], v142 offset:40960
	ds_read_b64_tr_b16 v[164:165], v142 offset:41472
	ds_read_b64_tr_b16 v[68:69], v140 offset:45056
	ds_read_b64_tr_b16 v[70:71], v141 offset:45056
	ds_read_b64_tr_b16 v[166:167], v142 offset:43008
	ds_read_b64_tr_b16 v[168:169], v142 offset:43520
	ds_read_b64_tr_b16 v[72:73], v140 offset:49152
	ds_read_b64_tr_b16 v[74:75], v141 offset:49152
	ds_read_b64_tr_b16 v[170:171], v142 offset:45056
	ds_read_b64_tr_b16 v[172:173], v142 offset:45568
	s_add_u32 s65, s54, 3
	s_min_u32 s65, s65, 67
	s_cmp_lt_u32 s65, 4
	s_cselect_b32 s0, s35, s55
	s_mul_i32 s1, s65, s80
	s_add_u32 s0, s0, s1
	s_mul_i32 s1, s0, s34
	s_add_u32 s6, s22, s1
	s_addc_u32 s7, s23, 0
	s_add_u32 s8, s24, s1
	s_addc_u32 s9, s25, 0
	s_mul_i32 s1, s0, 0x1840
	s_add_u32 s10, s26, s1
	s_addc_u32 s11, s27, 0
	s_lshr_b32 s1, s0, 6
	s_lshl_b32 s1, s1, 11
	s_add_u32 s18, s28, s1
	s_addc_u32 s19, s29, 0
	s_waitcnt lgkmcnt(8)
	v_mfma_f32_32x32x16_bf16 v[0:15], v[64:67], v[162:165], v[0:15]
	ds_read_b64_tr_b16 v[76:77], v140 offset:53248
	ds_read_b64_tr_b16 v[78:79], v141 offset:53248
	ds_read_b64_tr_b16 v[174:175], v142 offset:47104
	ds_read_b64_tr_b16 v[176:177], v142 offset:47616
	s_cmp_eq_u32 s96, 0
	s_cbranch_scc1 .Lgs1_nochain
	s_cmp_eq_u32 s76, 1
	s_cbranch_scc1 .Lgs1_nochain
	s_waitcnt lgkmcnt(8)
	v_mfma_f32_32x32x16_bf16 v[0:15], v[68:71], v[166:169], v[0:15]
	ds_read_b128 v[32:35], v220
	ds_read_b128 v[48:51], v221 offset:40960
	v_xor_b32_e32 v198, 32, v220
	v_xor_b32_e32 v199, 32, v221
	ds_read_b128 v[36:39], v198
	ds_read_b128 v[52:55], v199 offset:40960
	global_load_dwordx4 v[96:99], v134, s[6:7]
	s_waitcnt lgkmcnt(8)
	v_mfma_f32_32x32x16_bf16 v[0:15], v[72:75], v[170:173], v[0:15]
	v_xor_b32_e32 v198, 64, v220
	v_xor_b32_e32 v199, 64, v221
	ds_read_b128 v[40:43], v198
	ds_read_b128 v[56:59], v199 offset:40960
	v_xor_b32_e32 v198, 96, v220
	v_xor_b32_e32 v199, 96, v221
	ds_read_b128 v[44:47], v198
	ds_read_b128 v[60:63], v199 offset:40960
	global_load_dwordx4 v[100:103], v134, s[6:7] offset:128
	s_waitcnt lgkmcnt(8)
	v_mfma_f32_32x32x16_bf16 v[0:15], v[76:79], v[174:177], v[0:15]
	global_load_dwordx4 v[104:107], v134, s[8:9]
	s_waitcnt lgkmcnt(6)
	v_mfma_f32_32x32x16_bf16 v[146:161], v[32:35], v[48:51], 0
	v_xor_b32_e32 v198, 128, v220
	v_xor_b32_e32 v199, 128, v221
	ds_read_b128 v[32:35], v198
	ds_read_b128 v[48:51], v199 offset:40960
	global_load_dwordx4 v[108:111], v134, s[8:9] offset:128
	s_waitcnt lgkmcnt(6)
	v_mfma_f32_32x32x16_bf16 v[146:161], v[36:39], v[52:55], v[146:161]
	v_xor_b32_e32 v198, 160, v220
	v_xor_b32_e32 v199, 160, v221
	ds_read_b128 v[36:39], v198
	ds_read_b128 v[52:55], v199 offset:40960
	global_load_dwordx4 v[136:139], v135, s[10:11]
	s_waitcnt lgkmcnt(6)
	v_mfma_f32_32x32x16_bf16 v[146:161], v[40:43], v[56:59], v[146:161]
	v_xor_b32_e32 v198, 192, v220
	v_xor_b32_e32 v199, 192, v221
	ds_read_b128 v[40:43], v198
	ds_read_b128 v[56:59], v199 offset:40960
	global_load_dword v133, v145, s[18:19]
	s_waitcnt lgkmcnt(6)
	v_mfma_f32_32x32x16_bf16 v[146:161], v[44:47], v[60:63], v[146:161]
	v_xor_b32_e32 v198, 224, v220
	v_xor_b32_e32 v199, 224, v221
	ds_read_b128 v[44:47], v198
	ds_read_b128 v[60:63], v199 offset:40960
	s_waitcnt lgkmcnt(6)
	v_mfma_f32_32x32x16_bf16 v[146:161], v[32:35], v[48:51], v[146:161]
	ds_read_b128 v[178:181], v252 offset:512
	ds_read_b128 v[182:185], v252 offset:544
	ds_read_b128 v[186:189], v252 offset:576
	ds_read_b128 v[190:193], v252 offset:608
	s_waitcnt lgkmcnt(8)
	v_mfma_f32_32x32x16_bf16 v[146:161], v[36:39], v[52:55], v[146:161]
	s_waitcnt lgkmcnt(6)
	v_mfma_f32_32x32x16_bf16 v[146:161], v[40:43], v[56:59], v[146:161]
	s_waitcnt lgkmcnt(4)
	v_mfma_f32_32x32x16_bf16 v[146:161], v[44:47], v[60:63], v[146:161]
	s_cmp_eq_u32 s16, 0
	s_cbranch_scc1 .Lgs1_scale
	s_cmp_eq_u32 s76, 2
	s_cbranch_scc0 .Lgs1_scale
	v_xor_b32_e32 v198, 32, v249
	ds_read_b128 v[64:67], v249 offset:0
	ds_read_b128 v[68:71], v198 offset:0
	s_cmp_eq_u32 s77, 0
	s_cbranch_scc1 .Lgs1_ohalf
	v_xor_b32_e32 v199, 64, v249
	v_xor_b32_e32 v200, 96, v249
	ds_read_b128 v[72:75], v199 offset:0
	ds_read_b128 v[76:79], v200 offset:0
	s_waitcnt lgkmcnt(2)
	v_mfma_f32_32x32x16_bf16 v[16:31], v[80:83], v[64:67], v[16:31]
	v_mfma_f32_32x32x16_bf16 v[16:31], v[84:87], v[68:71], v[16:31]
	s_waitcnt lgkmcnt(0)
	v_mfma_f32_32x32x16_bf16 v[16:31], v[88:91], v[72:75], v[16:31]
	v_mfma_f32_32x32x16_bf16 v[16:31], v[92:95], v[76:79], v[16:31]
	s_branch .Lgs1_odone

; __device__ __forceinline__ void gla_scan_phase(const Params& p, int j, bool need_ctx, char* smem, int tid, int bid) {
;     ...
; #pragma unroll
;         for (int k16 = 0; k16 < 4; ++k16) Sacc = __builtin_amdgcn_mfma_f32_32x32x16_bf16(av[k16], bv4[k16], Sacc, 0, 0, 0);
; #pragma unroll
;         for (int rg = 0; rg < 4; ++rg) {
;           const f32x4 e4 = *(const f32x4*)(ebend + kb * 32 + 8 * rg + 4 * hi);
;           Sacc[rg * 4 + 0] *= e4[0]; Sacc[rg * 4 + 1] *= e4[1]; Sacc[rg * 4 + 2] *= e4[2]; Sacc[rg * 4 + 3] *= e4[3];
;         }
;     ...
;       {
;         const int dv = dvb2 * 32 + l32;
; #pragma unroll
;         for (int rg = 0; rg < 4; ++rg) {
;           const int k0 = kb * 32 + 8 * rg + 4 * hi;
;           u32x2 w = {cvtpk(Sacc[rg * 4 + 0], Sacc[rg * 4 + 1]), cvtpk(Sacc[rg * 4 + 2], Sacc[rg * 4 + 3])};
;           *(u32x2*)(STL + swz256(dv, k0 >> 3) + (k0 & 7) * 2) = w;
;         }
;       }
.Lgs1_scale:
	s_waitcnt lgkmcnt(0)
	v_pk_mul_f32 v[0:1], v[0:1], v[178:179]
	v_pk_mul_f32 v[2:3], v[2:3], v[180:181]
	v_pk_mul_f32 v[4:5], v[4:5], v[182:183]
	v_pk_mul_f32 v[6:7], v[6:7], v[184:185]
	v_pk_mul_f32 v[8:9], v[8:9], v[186:187]
	v_pk_mul_f32 v[10:11], v[10:11], v[188:189]
	v_pk_mul_f32 v[12:13], v[12:13], v[190:191]
	v_pk_mul_f32 v[14:15], v[14:15], v[192:193]
	v_cvt_pk_bf16_f32 v178, v0, v1
	v_cvt_pk_bf16_f32 v179, v2, v3
	v_cvt_pk_bf16_f32 v180, v4, v5
	v_cvt_pk_bf16_f32 v181, v6, v7
	v_cvt_pk_bf16_f32 v182, v8, v9
	v_cvt_pk_bf16_f32 v183, v10, v11
	v_cvt_pk_bf16_f32 v184, v12, v13
	v_cvt_pk_bf16_f32 v185, v14, v15
	v_xor_b32_e32 v198, 16, v250
	v_xor_b32_e32 v199, 32, v250
	v_xor_b32_e32 v200, 48, v250
	ds_write_b64 v250, v[178:179] offset:0
	ds_write_b64 v198, v[180:181] offset:0
	ds_write_b64 v199, v[182:183] offset:0
	ds_write_b64 v200, v[184:185] offset:0
	s_add_u32 s0, s97, s72
	s_cmp_eq_u32 s0, 4
	s_cbranch_scc1 .Lgs1_w16
	s_waitcnt vmcnt(12)
	s_branch .Lgs1_wd

; __device__ __forceinline__ u16 f2bf(float x) { return (u16)(cvtpk(x, 0.f) & 0xffffu); }
; __device__ __forceinline__ int crow(int r, int hi) { return (r & 3) + 8 * (r >> 2) + 4 * hi; }
; __device__ __forceinline__ void gla_scan_phase(const Params& p, int j, bool need_ctx, char* smem, int tid, int bid) {
;     ...
;           const int t = tb * 32 + l32;
; #pragma unroll
;           for (int rg = 0; rg < 4; ++rg) {
;             const int s0 = sb * 32 + 8 * rg + 4 * hi;
;             const float v0 = (s0 + 0 <= t) ? sacc[rg * 4 + 0] : 0.f, v1 = (s0 + 1 <= t) ? sacc[rg * 4 + 1] : 0.f;
;             const float v2 = (s0 + 2 <= t) ? sacc[rg * 4 + 2] : 0.f, v3 = (s0 + 3 <= t) ? sacc[rg * 4 + 3] : 0.f;
;             u32x2 w = {cvtpk(v0, v1), cvtpk(v2, v3)};
;             *(u32x2*)(scL + swz128(t, s0 >> 3) + (s0 & 7) * 2) = w;
;           }
;     ...
;         if (!is_ctx || need_ctx) {
;           u16* O = dir ? OB : OF;
; #pragma unroll
;           for (int r = 0; r < 16; ++r) {
;             const int pos = c * 64 + tbo * 32 + crow(r, hi);
;             const int tok = dir ? TT - 1 - pos : pos;
;             O[(size_t)(base + tok) * 1024 + h * 256 + dvs * 64 + dvbo * 32 + l32] = f2bf(oacc[r]);
;           }
;         }
.Lgs_noeb_b1:
	s_mov_b32 s72, s97
	s_mov_b32 s97, 0
	s_cmp_eq_u32 s76, 1
	s_cbranch_scc1 .Lgs1_next
	s_cmp_eq_u32 s76, 2
	s_cbranch_scc1 .Lgs1_otail
	s_cmp_eq_u32 s96, 0
	s_cbranch_scc1 .Lgs1_next
	v_cvt_pk_bf16_f32 v32, v146, v147
	v_cvt_pk_bf16_f32 v33, v148, v149
	v_cvt_pk_bf16_f32 v34, v150, v151
	v_cvt_pk_bf16_f32 v35, v152, v153
	v_cvt_pk_bf16_f32 v36, v154, v155
	v_cvt_pk_bf16_f32 v37, v156, v157
	v_cvt_pk_bf16_f32 v38, v158, v159
	v_cvt_pk_bf16_f32 v39, v160, v161
	v_and_b32_e32 v32, v204, v32
	v_and_b32_e32 v33, v205, v33
	v_and_b32_e32 v34, v206, v34
	v_and_b32_e32 v35, v207, v35
	v_and_b32_e32 v36, v208, v36
	v_and_b32_e32 v37, v209, v37
	v_and_b32_e32 v38, v210, v38
	v_and_b32_e32 v39, v211, v39
	v_xor_b32_e32 v198, 16, v249
	v_xor_b32_e32 v199, 32, v249
	v_xor_b32_e32 v200, 48, v249
	ds_write_b64 v249, v[32:33] offset:8192
	ds_write_b64 v198, v[34:35] offset:8192
	ds_write_b64 v199, v[36:37] offset:8192
	ds_write_b64 v200, v[38:39] offset:8192
	s_branch .Lgs1_next
.Lgs1_otail:
	s_cmp_eq_u32 s16, 0
	s_cbranch_scc1 .Lgs1_next
	s_add_i32 s65, s54, -1
	s_cmp_lt_u32 s65, 4
	s_cselect_b32 s0, s35, s55
	s_mul_i32 s1, s65, s80
	s_add_u32 s0, s0, s1
	s_lshl_b32 s1, s0, 11
	s_add_u32 s20, s30, s1
	s_addc_u32 s21, s31, 0
	v_cvt_pk_bf16_f32 v186, v16, v17
	v_cvt_pk_bf16_f32 v187, v18, v19
	v_cvt_pk_bf16_f32 v188, v20, v21
	v_cvt_pk_bf16_f32 v189, v22, v23
	v_cvt_pk_bf16_f32 v190, v24, v25
	v_cvt_pk_bf16_f32 v191, v26, v27
	v_cvt_pk_bf16_f32 v192, v28, v29
	v_cvt_pk_bf16_f32 v193, v30, v31
	s_nop 0
	v_permlane32_swap_b32_e32 v186, v188
	v_permlane32_swap_b32_e32 v187, v189
	v_permlane32_swap_b32_e32 v190, v192
	v_permlane32_swap_b32_e32 v191, v193
	global_store_dwordx4 v204, v[186:189], s[20:21]
	global_store_dwordx4 v204, v[190:193], s[20:21] offset:32
	s_mov_b32 s97, 2

; __device__ __forceinline__ void gla_scan_phase(const Params& p, int j, bool need_ctx, char* smem, int tid, int bid) {
;     ...
;       } else if (wid < 4) {
;         const int sb = wid & 1, tb = wid >> 1;
;         if (sb <= tb) {
;           f32x16 sacc;
; #pragma unroll
;           for (int r = 0; r < 16; ++r) sacc[r] = 0.f;
;           bf16x8 av[8], bv8[8];
; #pragma unroll
;           for (int k16 = 0; k16 < 8; ++k16) {
;             av[k16] = *(const bf16x8*)(kinvL + swz256(sb * 32 + l32, k16 * 2 + hi));
;             bv8[k16] = *(const bf16x8*)(qbL + swz256(tb * 32 + l32, k16 * 2 + hi));
;           }
; #pragma unroll
;           for (int k16 = 0; k16 < 8; ++k16) sacc = __builtin_amdgcn_mfma_f32_32x32x16_bf16(av[k16], bv8[k16], sacc, 0, 0, 0);
;           const int t = tb * 32 + l32;
; #pragma unroll
;           for (int rg = 0; rg < 4; ++rg) {
;             const int s0 = sb * 32 + 8 * rg + 4 * hi;
;             const float v0 = (s0 + 0 <= t) ? sacc[rg * 4 + 0] : 0.f, v1 = (s0 + 1 <= t) ? sacc[rg * 4 + 1] : 0.f;
;             const float v2 = (s0 + 2 <= t) ? sacc[rg * 4 + 2] : 0.f, v3 = (s0 + 3 <= t) ? sacc[rg * 4 + 3] : 0.f;
;             u32x2 w = {cvtpk(v0, v1), cvtpk(v2, v3)};
;             *(u32x2*)(scL + swz128(t, s0 >> 3) + (s0 & 7) * 2) = w;
;           }
;         }
;       } else {
;         bf16x8 av[8], bv8[8];
; #pragma unroll
;         for (int k16 = 0; k16 < 8; ++k16) {
;           av[k16] = *(const bf16x8*)(qbL + swz256(tbo * 32 + l32, k16 * 2 + hi));
;           bv8[k16] = *(const bf16x8*)(STL + swz256(dvbo * 32 + l32, k16 * 2 + hi));
;         }
; #pragma unroll
;         for (int k16 = 0; k16 < 8; ++k16) oacc = __builtin_amdgcn_mfma_f32_32x32x16_bf16(av[k16], bv8[k16], oacc, 0, 0, 0);
;       }
;       const int kb = wid >> 1, dvb2 = wid & 1;
;       {
;         bf16x8 av[4], bv4[4];
; #pragma unroll
;         for (int k16 = 0; k16 < 4; ++k16) {
;           av[k16] = *(const bf16x8*)(kendT + swz128(kb * 32 + l32, k16 * 2 + hi));
;           bv4[k16] = *(const bf16x8*)(vT + swz128(dvb2 * 32 + l32, k16 * 2 + hi));
;         }
; #pragma unroll
;         for (int k16 = 0; k16 < 4; ++k16) Sacc = __builtin_amdgcn_mfma_f32_32x32x16_bf16(av[k16], bv4[k16], Sacc, 0, 0, 0);
; #pragma unroll
;         for (int rg = 0; rg < 4; ++rg) {
;           const f32x4 e4 = *(const f32x4*)(ebend + kb * 32 + 8 * rg + 4 * hi);
.Lgs2_chunk:
	s_cmp_gt_u32 s54, 3
	s_cselect_b32 s96, 1, s60
	s_waitcnt lgkmcnt(0)
	s_barrier
	s_cmp_eq_u32 s54, 68
	s_cbranch_scc1 .Lgs_tail
	ds_read_b64_tr_b16 v[64:65], v140 offset:0
	ds_read_b64_tr_b16 v[66:67], v141 offset:0
	ds_read_b64_tr_b16 v[80:81], v142 offset:0
	ds_read_b64_tr_b16 v[82:83], v142 offset:512
	ds_read_b64_tr_b16 v[68:69], v140 offset:4096
	ds_read_b64_tr_b16 v[70:71], v141 offset:4096
	ds_read_b64_tr_b16 v[84:85], v142 offset:2048
	ds_read_b64_tr_b16 v[86:87], v142 offset:2560
	ds_read_b64_tr_b16 v[72:73], v140 offset:8192
	ds_read_b64_tr_b16 v[74:75], v141 offset:8192
	ds_read_b64_tr_b16 v[88:89], v142 offset:4096
	ds_read_b64_tr_b16 v[90:91], v142 offset:4608
	s_add_u32 s65, s54, 3
	s_min_u32 s65, s65, 67
	s_cmp_lt_u32 s65, 4
	s_cselect_b32 s0, s35, s55
	s_mul_i32 s1, s65, s80
	s_add_u32 s0, s0, s1
	s_mul_i32 s1, s0, s34
	s_add_u32 s6, s22, s1
	s_addc_u32 s7, s23, 0
	s_add_u32 s8, s24, s1
	s_addc_u32 s9, s25, 0
	s_mul_i32 s1, s0, 0x1840
	s_add_u32 s10, s26, s1
	s_addc_u32 s11, s27, 0
	s_lshr_b32 s1, s0, 6
	s_lshl_b32 s1, s1, 11
	s_add_u32 s18, s28, s1
	s_addc_u32 s19, s29, 0
	s_waitcnt lgkmcnt(8)
	v_mfma_f32_32x32x16_bf16 v[0:15], v[64:67], v[80:83], v[0:15]
	ds_read_b64_tr_b16 v[76:77], v140 offset:12288
	ds_read_b64_tr_b16 v[78:79], v141 offset:12288
	ds_read_b64_tr_b16 v[92:93], v142 offset:6144
	ds_read_b64_tr_b16 v[94:95], v142 offset:6656
	s_cmp_eq_u32 s96, 0
	s_cbranch_scc1 .Lgs2_nochain
	s_cmp_eq_u32 s76, 1
	s_cbranch_scc1 .Lgs2_nochain
	s_waitcnt lgkmcnt(8)
	v_mfma_f32_32x32x16_bf16 v[0:15], v[68:71], v[84:87], v[0:15]
	ds_read_b128 v[32:35], v243
	ds_read_b128 v[48:51], v221 offset:0
	v_xor_b32_e32 v198, 32, v243
	v_xor_b32_e32 v199, 32, v221
	ds_read_b128 v[36:39], v198
	ds_read_b128 v[52:55], v199 offset:0
	global_load_dwordx4 v[222:225], v134, s[6:7]
	s_waitcnt lgkmcnt(8)
	v_mfma_f32_32x32x16_bf16 v[0:15], v[72:75], v[88:91], v[0:15]
	v_xor_b32_e32 v198, 64, v243
	v_xor_b32_e32 v199, 64, v221
	ds_read_b128 v[40:43], v198
	ds_read_b128 v[56:59], v199 offset:0
	v_xor_b32_e32 v198, 96, v243
	v_xor_b32_e32 v199, 96, v221
	ds_read_b128 v[44:47], v198
	ds_read_b128 v[60:63], v199 offset:0
	global_load_dwordx4 v[226:229], v134, s[6:7] offset:128
	s_waitcnt lgkmcnt(8)
	v_mfma_f32_32x32x16_bf16 v[0:15], v[76:79], v[92:95], v[0:15]
	global_load_dwordx4 v[230:233], v134, s[8:9]
	s_waitcnt lgkmcnt(6)
	v_mfma_f32_32x32x16_bf16 v[16:31], v[32:35], v[48:51], 0
	v_xor_b32_e32 v198, 128, v243
	v_xor_b32_e32 v199, 128, v221
	ds_read_b128 v[32:35], v198
	ds_read_b128 v[48:51], v199 offset:0
	global_load_dwordx4 v[234:237], v134, s[8:9] offset:128
	s_waitcnt lgkmcnt(6)
	v_mfma_f32_32x32x16_bf16 v[16:31], v[36:39], v[52:55], v[16:31]
	v_xor_b32_e32 v198, 160, v243
	v_xor_b32_e32 v199, 160, v221
	ds_read_b128 v[36:39], v198
	ds_read_b128 v[52:55], v199 offset:0
	global_load_dwordx4 v[244:247], v135, s[10:11]
	s_waitcnt lgkmcnt(6)
	v_mfma_f32_32x32x16_bf16 v[16:31], v[40:43], v[56:59], v[16:31]
	v_xor_b32_e32 v198, 192, v243
	v_xor_b32_e32 v199, 192, v221
	ds_read_b128 v[40:43], v198
	ds_read_b128 v[56:59], v199 offset:0
	global_load_dword v248, v145, s[18:19]
	s_waitcnt lgkmcnt(6)
	v_mfma_f32_32x32x16_bf16 v[16:31], v[44:47], v[60:63], v[16:31]
	v_xor_b32_e32 v198, 224, v243
	v_xor_b32_e32 v199, 224, v221
	ds_read_b128 v[44:47], v198
	ds_read_b128 v[60:63], v199 offset:0
	s_waitcnt lgkmcnt(6)
	v_mfma_f32_32x32x16_bf16 v[16:31], v[32:35], v[48:51], v[16:31]
	ds_read_b128 v[178:181], v252 offset:0
	ds_read_b128 v[182:185], v252 offset:32
	ds_read_b128 v[186:189], v252 offset:64
	ds_read_b128 v[190:193], v252 offset:96
	s_waitcnt lgkmcnt(8)
	v_mfma_f32_32x32x16_bf16 v[16:31], v[36:39], v[52:55], v[16:31]
	s_waitcnt lgkmcnt(6)
	v_mfma_f32_32x32x16_bf16 v[16:31], v[40:43], v[56:59], v[16:31]
	s_waitcnt lgkmcnt(4)
	v_mfma_f32_32x32x16_bf16 v[16:31], v[44:47], v[60:63], v[16:31]
	s_cmp_eq_u32 s16, 0
	s_cbranch_scc1 .Lgs2_scale
	s_cmp_eq_u32 s76, 2
	s_cbranch_scc0 .Lgs2_scale
	v_xor_b32_e32 v198, 32, v249
	ds_read_b128 v[64:67], v249 offset:8192
	ds_read_b128 v[68:71], v198 offset:8192
	s_cmp_eq_u32 s77, 0
	s_cbranch_scc1 .Lgs2_ohalf
	v_xor_b32_e32 v199, 64, v249
	v_xor_b32_e32 v200, 96, v249
	ds_read_b128 v[72:75], v199 offset:8192
	ds_read_b128 v[76:79], v200 offset:8192
	s_waitcnt lgkmcnt(2)
	v_mfma_f32_32x32x16_bf16 v[146:161], v[162:165], v[64:67], v[146:161]
	v_mfma_f32_32x32x16_bf16 v[146:161], v[166:169], v[68:71], v[146:161]
	s_waitcnt lgkmcnt(0)
	v_mfma_f32_32x32x16_bf16 v[146:161], v[170:173], v[72:75], v[146:161]
	v_mfma_f32_32x32x16_bf16 v[146:161], v[174:177], v[76:79], v[146:161]
	s_branch .Lgs2_odone

; __device__ __forceinline__ void gla_scan_phase(const Params& p, int j, bool need_ctx, char* smem, int tid, int bid) {
;     ...
;       } else if (wid < 4) {
;         const int sb = wid & 1, tb = wid >> 1;
;         if (sb <= tb) {
;           f32x16 sacc;
; #pragma unroll
;           for (int r = 0; r < 16; ++r) sacc[r] = 0.f;
;           bf16x8 av[8], bv8[8];
; #pragma unroll
;           for (int k16 = 0; k16 < 8; ++k16) {
;             av[k16] = *(const bf16x8*)(kinvL + swz256(sb * 32 + l32, k16 * 2 + hi));
;             bv8[k16] = *(const bf16x8*)(qbL + swz256(tb * 32 + l32, k16 * 2 + hi));
;           }
; #pragma unroll
;           for (int k16 = 0; k16 < 8; ++k16) sacc = __builtin_amdgcn_mfma_f32_32x32x16_bf16(av[k16], bv8[k16], sacc, 0, 0, 0);
;           const int t = tb * 32 + l32;
; #pragma unroll
;           for (int rg = 0; rg < 4; ++rg) {
;             const int s0 = sb * 32 + 8 * rg + 4 * hi;
;             const float v0 = (s0 + 0 <= t) ? sacc[rg * 4 + 0] : 0.f, v1 = (s0 + 1 <= t) ? sacc[rg * 4 + 1] : 0.f;
;             const float v2 = (s0 + 2 <= t) ? sacc[rg * 4 + 2] : 0.f, v3 = (s0 + 3 <= t) ? sacc[rg * 4 + 3] : 0.f;
;             u32x2 w = {cvtpk(v0, v1), cvtpk(v2, v3)};
;             *(u32x2*)(scL + swz128(t, s0 >> 3) + (s0 & 7) * 2) = w;
;           }
;         }
;       } else {
;         bf16x8 av[8], bv8[8];
; #pragma unroll
;         for (int k16 = 0; k16 < 8; ++k16) {
;           av[k16] = *(const bf16x8*)(qbL + swz256(tbo * 32 + l32, k16 * 2 + hi));
;           bv8[k16] = *(const bf16x8*)(STL + swz256(dvbo * 32 + l32, k16 * 2 + hi));
;         }
; #pragma unroll
;         for (int k16 = 0; k16 < 8; ++k16) oacc = __builtin_amdgcn_mfma_f32_32x32x16_bf16(av[k16], bv8[k16], oacc, 0, 0, 0);
;       }
;       const int kb = wid >> 1, dvb2 = wid & 1;
;       {
;         bf16x8 av[4], bv4[4];
; #pragma unroll
;         for (int k16 = 0; k16 < 4; ++k16) {
;           av[k16] = *(const bf16x8*)(kendT + swz128(kb * 32 + l32, k16 * 2 + hi));
;           bv4[k16] = *(const bf16x8*)(vT + swz128(dvb2 * 32 + l32, k16 * 2 + hi));
;         }
; #pragma unroll
;         for (int k16 = 0; k16 < 4; ++k16) Sacc = __builtin_amdgcn_mfma_f32_32x32x16_bf16(av[k16], bv4[k16], Sacc, 0, 0, 0);
; #pragma unroll
;         for (int rg = 0; rg < 4; ++rg) {
;           const f32x4 e4 = *(const f32x4*)(ebend + kb * 32 + 8 * rg + 4 * hi);
.Lgs3_chunk:
	s_cmp_gt_u32 s54, 3
	s_cselect_b32 s96, 1, s60
	s_waitcnt lgkmcnt(0)
	s_barrier
	ds_read_b64_tr_b16 v[64:65], v140 offset:40960
	ds_read_b64_tr_b16 v[66:67], v141 offset:40960
	ds_read_b64_tr_b16 v[162:163], v142 offset:40960
	ds_read_b64_tr_b16 v[164:165], v142 offset:41472
	ds_read_b64_tr_b16 v[68:69], v140 offset:45056
	ds_read_b64_tr_b16 v[70:71], v141 offset:45056
	ds_read_b64_tr_b16 v[166:167], v142 offset:43008
	ds_read_b64_tr_b16 v[168:169], v142 offset:43520
	ds_read_b64_tr_b16 v[72:73], v140 offset:49152
	ds_read_b64_tr_b16 v[74:75], v141 offset:49152
	ds_read_b64_tr_b16 v[170:171], v142 offset:45056
	ds_read_b64_tr_b16 v[172:173], v142 offset:45568
	s_add_u32 s65, s54, 3
	s_min_u32 s65, s65, 67
	s_cmp_lt_u32 s65, 4
	s_cselect_b32 s0, s35, s55
	s_mul_i32 s1, s65, s80
	s_add_u32 s0, s0, s1
	s_mul_i32 s1, s0, s34
	s_add_u32 s6, s22, s1
	s_addc_u32 s7, s23, 0
	s_add_u32 s8, s24, s1
	s_addc_u32 s9, s25, 0
	s_mul_i32 s1, s0, 0x1840
	s_add_u32 s10, s26, s1
	s_addc_u32 s11, s27, 0
	s_lshr_b32 s1, s0, 6
	s_lshl_b32 s1, s1, 11
	s_add_u32 s18, s28, s1
	s_addc_u32 s19, s29, 0
	s_waitcnt lgkmcnt(8)
	v_mfma_f32_32x32x16_bf16 v[0:15], v[64:67], v[162:165], v[0:15]
	ds_read_b64_tr_b16 v[76:77], v140 offset:53248
	ds_read_b64_tr_b16 v[78:79], v141 offset:53248
	ds_read_b64_tr_b16 v[174:175], v142 offset:47104
	ds_read_b64_tr_b16 v[176:177], v142 offset:47616
	s_cmp_eq_u32 s96, 0
	s_cbranch_scc1 .Lgs3_nochain
	s_cmp_eq_u32 s76, 1
	s_cbranch_scc1 .Lgs3_nochain
	s_waitcnt lgkmcnt(8)
	v_mfma_f32_32x32x16_bf16 v[0:15], v[68:71], v[166:169], v[0:15]
	ds_read_b128 v[32:35], v220
	ds_read_b128 v[48:51], v221 offset:40960
	v_xor_b32_e32 v198, 32, v220
	v_xor_b32_e32 v199, 32, v221
	ds_read_b128 v[36:39], v198
	ds_read_b128 v[52:55], v199 offset:40960
	global_load_dwordx4 v[112:115], v134, s[6:7]
	s_waitcnt lgkmcnt(8)
	v_mfma_f32_32x32x16_bf16 v[0:15], v[72:75], v[170:173], v[0:15]
	v_xor_b32_e32 v198, 64, v220
	v_xor_b32_e32 v199, 64, v221
	ds_read_b128 v[40:43], v198
	ds_read_b128 v[56:59], v199 offset:40960
	v_xor_b32_e32 v198, 96, v220
	v_xor_b32_e32 v199, 96, v221
	ds_read_b128 v[44:47], v198
	ds_read_b128 v[60:63], v199 offset:40960
	global_load_dwordx4 v[116:119], v134, s[6:7] offset:128
	s_waitcnt lgkmcnt(8)
	v_mfma_f32_32x32x16_bf16 v[0:15], v[76:79], v[174:177], v[0:15]
	global_load_dwordx4 v[120:123], v134, s[8:9]
	s_waitcnt lgkmcnt(6)
	v_mfma_f32_32x32x16_bf16 v[146:161], v[32:35], v[48:51], 0
	v_xor_b32_e32 v198, 128, v220
	v_xor_b32_e32 v199, 128, v221
	ds_read_b128 v[32:35], v198
	ds_read_b128 v[48:51], v199 offset:40960
	global_load_dwordx4 v[124:127], v134, s[8:9] offset:128
	s_waitcnt lgkmcnt(6)
	v_mfma_f32_32x32x16_bf16 v[146:161], v[36:39], v[52:55], v[146:161]
	v_xor_b32_e32 v198, 160, v220
	v_xor_b32_e32 v199, 160, v221
	ds_read_b128 v[36:39], v198
	ds_read_b128 v[52:55], v199 offset:40960
	global_load_dwordx4 v[128:131], v135, s[10:11]
	s_waitcnt lgkmcnt(6)
	v_mfma_f32_32x32x16_bf16 v[146:161], v[40:43], v[56:59], v[146:161]
	v_xor_b32_e32 v198, 192, v220
	v_xor_b32_e32 v199, 192, v221
	ds_read_b128 v[40:43], v198
	ds_read_b128 v[56:59], v199 offset:40960
	global_load_dword v132, v145, s[18:19]
	s_waitcnt lgkmcnt(6)
	v_mfma_f32_32x32x16_bf16 v[146:161], v[44:47], v[60:63], v[146:161]
	v_xor_b32_e32 v198, 224, v220
	v_xor_b32_e32 v199, 224, v221
	ds_read_b128 v[44:47], v198
	ds_read_b128 v[60:63], v199 offset:40960
	s_waitcnt lgkmcnt(6)
	v_mfma_f32_32x32x16_bf16 v[146:161], v[32:35], v[48:51], v[146:161]
	ds_read_b128 v[178:181], v252 offset:512
	ds_read_b128 v[182:185], v252 offset:544
	ds_read_b128 v[186:189], v252 offset:576
	ds_read_b128 v[190:193], v252 offset:608
	s_waitcnt lgkmcnt(8)
	v_mfma_f32_32x32x16_bf16 v[146:161], v[36:39], v[52:55], v[146:161]
	s_waitcnt lgkmcnt(6)
	v_mfma_f32_32x32x16_bf16 v[146:161], v[40:43], v[56:59], v[146:161]
	s_waitcnt lgkmcnt(4)
	v_mfma_f32_32x32x16_bf16 v[146:161], v[44:47], v[60:63], v[146:161]
	s_cmp_eq_u32 s16, 0
	s_cbranch_scc1 .Lgs3_scale
	s_cmp_eq_u32 s76, 2
	s_cbranch_scc0 .Lgs3_scale
	v_xor_b32_e32 v198, 32, v249
	ds_read_b128 v[64:67], v249 offset:0
	ds_read_b128 v[68:71], v198 offset:0
	s_cmp_eq_u32 s77, 0
	s_cbranch_scc1 .Lgs3_ohalf
	v_xor_b32_e32 v199, 64, v249
	v_xor_b32_e32 v200, 96, v249
	ds_read_b128 v[72:75], v199 offset:0
	ds_read_b128 v[76:79], v200 offset:0
	s_waitcnt lgkmcnt(2)
	v_mfma_f32_32x32x16_bf16 v[16:31], v[80:83], v[64:67], v[16:31]
	v_mfma_f32_32x32x16_bf16 v[16:31], v[84:87], v[68:71], v[16:31]
	s_waitcnt lgkmcnt(0)
	v_mfma_f32_32x32x16_bf16 v[16:31], v[88:91], v[72:75], v[16:31]
	v_mfma_f32_32x32x16_bf16 v[16:31], v[92:95], v[76:79], v[16:31]
	s_branch .Lgs3_odone

; __device__ __forceinline__ void gla_scan_phase(const Params& p, int j, bool need_ctx, char* smem, int tid, int bid) {
;     ...
;       } else if (wid < 4) {
;         const int sb = wid & 1, tb = wid >> 1;
;         if (sb <= tb) {
;           f32x16 sacc;
; #pragma unroll
;           for (int r = 0; r < 16; ++r) sacc[r] = 0.f;
;           bf16x8 av[8], bv8[8];
; #pragma unroll
;           for (int k16 = 0; k16 < 8; ++k16) {
;             av[k16] = *(const bf16x8*)(kinvL + swz256(sb * 32 + l32, k16 * 2 + hi));
;             bv8[k16] = *(const bf16x8*)(qbL + swz256(tb * 32 + l32, k16 * 2 + hi));
;           }
; #pragma unroll
;           for (int k16 = 0; k16 < 8; ++k16) sacc = __builtin_amdgcn_mfma_f32_32x32x16_bf16(av[k16], bv8[k16], sacc, 0, 0, 0);
;           const int t = tb * 32 + l32;
; #pragma unroll
;           for (int rg = 0; rg < 4; ++rg) {
;             const int s0 = sb * 32 + 8 * rg + 4 * hi;
;             const float v0 = (s0 + 0 <= t) ? sacc[rg * 4 + 0] : 0.f, v1 = (s0 + 1 <= t) ? sacc[rg * 4 + 1] : 0.f;
;             const float v2 = (s0 + 2 <= t) ? sacc[rg * 4 + 2] : 0.f, v3 = (s0 + 3 <= t) ? sacc[rg * 4 + 3] : 0.f;
;             u32x2 w = {cvtpk(v0, v1), cvtpk(v2, v3)};
;             *(u32x2*)(scL + swz128(t, s0 >> 3) + (s0 & 7) * 2) = w;
;           }
;         }
;       } else {
;         bf16x8 av[8], bv8[8];
; #pragma unroll
;         for (int k16 = 0; k16 < 8; ++k16) {
;           av[k16] = *(const bf16x8*)(qbL + swz256(tbo * 32 + l32, k16 * 2 + hi));
;           bv8[k16] = *(const bf16x8*)(STL + swz256(dvbo * 32 + l32, k16 * 2 + hi));
;         }
; #pragma unroll
;         for (int k16 = 0; k16 < 8; ++k16) oacc = __builtin_amdgcn_mfma_f32_32x32x16_bf16(av[k16], bv8[k16], oacc, 0, 0, 0);
;       }
;       const int kb = wid >> 1, dvb2 = wid & 1;
;       {
;         bf16x8 av[4], bv4[4];
; #pragma unroll
;         for (int k16 = 0; k16 < 4; ++k16) {
;           av[k16] = *(const bf16x8*)(kendT + swz128(kb * 32 + l32, k16 * 2 + hi));
;           bv4[k16] = *(const bf16x8*)(vT + swz128(dvb2 * 32 + l32, k16 * 2 + hi));
;         }
; #pragma unroll
;         for (int k16 = 0; k16 < 4; ++k16) Sacc = __builtin_amdgcn_mfma_f32_32x32x16_bf16(av[k16], bv4[k16], Sacc, 0, 0, 0);
; #pragma unroll
;         for (int rg = 0; rg < 4; ++rg) {
;           const f32x4 e4 = *(const f32x4*)(ebend + kb * 32 + 8 * rg + 4 * hi);
.Lgs4_chunk:
	s_cmp_gt_u32 s54, 3
	s_cselect_b32 s96, 1, s60
	s_waitcnt lgkmcnt(0)
	s_barrier
	ds_read_b64_tr_b16 v[64:65], v140 offset:0
	ds_read_b64_tr_b16 v[66:67], v141 offset:0
	ds_read_b64_tr_b16 v[80:81], v142 offset:0
	ds_read_b64_tr_b16 v[82:83], v142 offset:512
	ds_read_b64_tr_b16 v[68:69], v140 offset:4096
	ds_read_b64_tr_b16 v[70:71], v141 offset:4096
	ds_read_b64_tr_b16 v[84:85], v142 offset:2048
	ds_read_b64_tr_b16 v[86:87], v142 offset:2560
	ds_read_b64_tr_b16 v[72:73], v140 offset:8192
	ds_read_b64_tr_b16 v[74:75], v141 offset:8192
	ds_read_b64_tr_b16 v[88:89], v142 offset:4096
	ds_read_b64_tr_b16 v[90:91], v142 offset:4608
	s_add_u32 s65, s54, 3
	s_min_u32 s65, s65, 67
	s_cmp_lt_u32 s65, 4
	s_cselect_b32 s0, s35, s55
	s_mul_i32 s1, s65, s80
	s_add_u32 s0, s0, s1
	s_mul_i32 s1, s0, s34
	s_add_u32 s6, s22, s1
	s_addc_u32 s7, s23, 0
	s_add_u32 s8, s24, s1
	s_addc_u32 s9, s25, 0
	s_mul_i32 s1, s0, 0x1840
	s_add_u32 s10, s26, s1
	s_addc_u32 s11, s27, 0
	s_lshr_b32 s1, s0, 6
	s_lshl_b32 s1, s1, 11
	s_add_u32 s18, s28, s1
	s_addc_u32 s19, s29, 0
	s_waitcnt lgkmcnt(8)
	v_mfma_f32_32x32x16_bf16 v[0:15], v[64:67], v[80:83], v[0:15]
	ds_read_b64_tr_b16 v[76:77], v140 offset:12288
	ds_read_b64_tr_b16 v[78:79], v141 offset:12288
	ds_read_b64_tr_b16 v[92:93], v142 offset:6144
	ds_read_b64_tr_b16 v[94:95], v142 offset:6656
	s_cmp_eq_u32 s96, 0
	s_cbranch_scc1 .Lgs4_nochain
	s_cmp_eq_u32 s76, 1
	s_cbranch_scc1 .Lgs4_nochain
	s_waitcnt lgkmcnt(8)
	v_mfma_f32_32x32x16_bf16 v[0:15], v[68:71], v[84:87], v[0:15]
	ds_read_b128 v[32:35], v243
	ds_read_b128 v[48:51], v221 offset:0
	v_xor_b32_e32 v198, 32, v243
	v_xor_b32_e32 v199, 32, v221
	ds_read_b128 v[36:39], v198
	ds_read_b128 v[52:55], v199 offset:0
	global_load_dwordx4 v[96:99], v134, s[6:7]
	s_waitcnt lgkmcnt(8)
	v_mfma_f32_32x32x16_bf16 v[0:15], v[72:75], v[88:91], v[0:15]
	v_xor_b32_e32 v198, 64, v243
	v_xor_b32_e32 v199, 64, v221
	ds_read_b128 v[40:43], v198
	ds_read_b128 v[56:59], v199 offset:0
	v_xor_b32_e32 v198, 96, v243
	v_xor_b32_e32 v199, 96, v221
	ds_read_b128 v[44:47], v198
	ds_read_b128 v[60:63], v199 offset:0
	global_load_dwordx4 v[100:103], v134, s[6:7] offset:128
	s_waitcnt lgkmcnt(8)
	v_mfma_f32_32x32x16_bf16 v[0:15], v[76:79], v[92:95], v[0:15]
	global_load_dwordx4 v[104:107], v134, s[8:9]
	s_waitcnt lgkmcnt(6)
	v_mfma_f32_32x32x16_bf16 v[16:31], v[32:35], v[48:51], 0
	v_xor_b32_e32 v198, 128, v243
	v_xor_b32_e32 v199, 128, v221
	ds_read_b128 v[32:35], v198
	ds_read_b128 v[48:51], v199 offset:0
	global_load_dwordx4 v[108:111], v134, s[8:9] offset:128
	s_waitcnt lgkmcnt(6)
	v_mfma_f32_32x32x16_bf16 v[16:31], v[36:39], v[52:55], v[16:31]
	v_xor_b32_e32 v198, 160, v243
	v_xor_b32_e32 v199, 160, v221
	ds_read_b128 v[36:39], v198
	ds_read_b128 v[52:55], v199 offset:0
	global_load_dwordx4 v[136:139], v135, s[10:11]
	s_waitcnt lgkmcnt(6)
	v_mfma_f32_32x32x16_bf16 v[16:31], v[40:43], v[56:59], v[16:31]
	v_xor_b32_e32 v198, 192, v243
	v_xor_b32_e32 v199, 192, v221
	ds_read_b128 v[40:43], v198
	ds_read_b128 v[56:59], v199 offset:0
	global_load_dword v133, v145, s[18:19]
	s_waitcnt lgkmcnt(6)
	v_mfma_f32_32x32x16_bf16 v[16:31], v[44:47], v[60:63], v[16:31]
	v_xor_b32_e32 v198, 224, v243
	v_xor_b32_e32 v199, 224, v221
	ds_read_b128 v[44:47], v198
	ds_read_b128 v[60:63], v199 offset:0
	s_waitcnt lgkmcnt(6)
	v_mfma_f32_32x32x16_bf16 v[16:31], v[32:35], v[48:51], v[16:31]
	ds_read_b128 v[178:181], v252 offset:0
	ds_read_b128 v[182:185], v252 offset:32
	ds_read_b128 v[186:189], v252 offset:64
	ds_read_b128 v[190:193], v252 offset:96
	s_waitcnt lgkmcnt(8)
	v_mfma_f32_32x32x16_bf16 v[16:31], v[36:39], v[52:55], v[16:31]
	s_waitcnt lgkmcnt(6)
	v_mfma_f32_32x32x16_bf16 v[16:31], v[40:43], v[56:59], v[16:31]
	s_waitcnt lgkmcnt(4)
	v_mfma_f32_32x32x16_bf16 v[16:31], v[44:47], v[60:63], v[16:31]
	s_cmp_eq_u32 s16, 0
	s_cbranch_scc1 .Lgs4_scale
	s_cmp_eq_u32 s76, 2
	s_cbranch_scc0 .Lgs4_scale
	v_xor_b32_e32 v198, 32, v249
	ds_read_b128 v[64:67], v249 offset:8192
	ds_read_b128 v[68:71], v198 offset:8192
	s_cmp_eq_u32 s77, 0
	s_cbranch_scc1 .Lgs4_ohalf
	v_xor_b32_e32 v199, 64, v249
	v_xor_b32_e32 v200, 96, v249
	ds_read_b128 v[72:75], v199 offset:8192
	ds_read_b128 v[76:79], v200 offset:8192
	s_waitcnt lgkmcnt(2)
	v_mfma_f32_32x32x16_bf16 v[146:161], v[162:165], v[64:67], v[146:161]
	v_mfma_f32_32x32x16_bf16 v[146:161], v[166:169], v[68:71], v[146:161]
	s_waitcnt lgkmcnt(0)
	v_mfma_f32_32x32x16_bf16 v[146:161], v[170:173], v[72:75], v[146:161]
	v_mfma_f32_32x32x16_bf16 v[146:161], v[174:177], v[76:79], v[146:161]
	s_branch .Lgs4_odone

; __device__ __forceinline__ void gla_scan_phase(const Params& p, int j, bool need_ctx, char* smem, int tid, int bid) {
;     ...
;       } else if (wid < 4) {
;         const int sb = wid & 1, tb = wid >> 1;
;         if (sb <= tb) {
;           f32x16 sacc;
; #pragma unroll
;           for (int r = 0; r < 16; ++r) sacc[r] = 0.f;
;           bf16x8 av[8], bv8[8];
; #pragma unroll
;           for (int k16 = 0; k16 < 8; ++k16) {
;             av[k16] = *(const bf16x8*)(kinvL + swz256(sb * 32 + l32, k16 * 2 + hi));
;             bv8[k16] = *(const bf16x8*)(qbL + swz256(tb * 32 + l32, k16 * 2 + hi));
;           }
; #pragma unroll
;           for (int k16 = 0; k16 < 8; ++k16) sacc = __builtin_amdgcn_mfma_f32_32x32x16_bf16(av[k16], bv8[k16], sacc, 0, 0, 0);
;           const int t = tb * 32 + l32;
; #pragma unroll
;           for (int rg = 0; rg < 4; ++rg) {
;             const int s0 = sb * 32 + 8 * rg + 4 * hi;
;             const float v0 = (s0 + 0 <= t) ? sacc[rg * 4 + 0] : 0.f, v1 = (s0 + 1 <= t) ? sacc[rg * 4 + 1] : 0.f;
;             const float v2 = (s0 + 2 <= t) ? sacc[rg * 4 + 2] : 0.f, v3 = (s0 + 3 <= t) ? sacc[rg * 4 + 3] : 0.f;
;             u32x2 w = {cvtpk(v0, v1), cvtpk(v2, v3)};
;             *(u32x2*)(scL + swz128(t, s0 >> 3) + (s0 & 7) * 2) = w;
;           }
;         }
;       } else {
;         bf16x8 av[8], bv8[8];
; #pragma unroll
;         for (int k16 = 0; k16 < 8; ++k16) {
;           av[k16] = *(const bf16x8*)(qbL + swz256(tbo * 32 + l32, k16 * 2 + hi));
;           bv8[k16] = *(const bf16x8*)(STL + swz256(dvbo * 32 + l32, k16 * 2 + hi));
;         }
; #pragma unroll
;         for (int k16 = 0; k16 < 8; ++k16) oacc = __builtin_amdgcn_mfma_f32_32x32x16_bf16(av[k16], bv8[k16], oacc, 0, 0, 0);
;       }
;       const int kb = wid >> 1, dvb2 = wid & 1;
;       {
;         bf16x8 av[4], bv4[4];
; #pragma unroll
;         for (int k16 = 0; k16 < 4; ++k16) {
;           av[k16] = *(const bf16x8*)(kendT + swz128(kb * 32 + l32, k16 * 2 + hi));
;           bv4[k16] = *(const bf16x8*)(vT + swz128(dvb2 * 32 + l32, k16 * 2 + hi));
;         }
; #pragma unroll
;         for (int k16 = 0; k16 < 4; ++k16) Sacc = __builtin_amdgcn_mfma_f32_32x32x16_bf16(av[k16], bv4[k16], Sacc, 0, 0, 0);
; #pragma unroll
;         for (int rg = 0; rg < 4; ++rg) {
;           const f32x4 e4 = *(const f32x4*)(ebend + kb * 32 + 8 * rg + 4 * hi);
.Lgs5_chunk:
	s_cmp_gt_u32 s54, 3
	s_cselect_b32 s96, 1, s60
	s_waitcnt lgkmcnt(0)
	s_barrier
	ds_read_b64_tr_b16 v[64:65], v140 offset:40960
	ds_read_b64_tr_b16 v[66:67], v141 offset:40960
	ds_read_b64_tr_b16 v[162:163], v142 offset:40960
	ds_read_b64_tr_b16 v[164:165], v142 offset:41472
	ds_read_b64_tr_b16 v[68:69], v140 offset:45056
	ds_read_b64_tr_b16 v[70:71], v141 offset:45056
	ds_read_b64_tr_b16 v[166:167], v142 offset:43008
	ds_read_b64_tr_b16 v[168:169], v142 offset:43520
	ds_read_b64_tr_b16 v[72:73], v140 offset:49152
	ds_read_b64_tr_b16 v[74:75], v141 offset:49152
	ds_read_b64_tr_b16 v[170:171], v142 offset:45056
	ds_read_b64_tr_b16 v[172:173], v142 offset:45568
	s_add_u32 s65, s54, 3
	s_min_u32 s65, s65, 67
	s_cmp_lt_u32 s65, 4
	s_cselect_b32 s0, s35, s55
	s_mul_i32 s1, s65, s80
	s_add_u32 s0, s0, s1
	s_mul_i32 s1, s0, s34
	s_add_u32 s6, s22, s1
	s_addc_u32 s7, s23, 0
	s_add_u32 s8, s24, s1
	s_addc_u32 s9, s25, 0
	s_mul_i32 s1, s0, 0x1840
	s_add_u32 s10, s26, s1
	s_addc_u32 s11, s27, 0
	s_lshr_b32 s1, s0, 6
	s_lshl_b32 s1, s1, 11
	s_add_u32 s18, s28, s1
	s_addc_u32 s19, s29, 0
	s_waitcnt lgkmcnt(8)
	v_mfma_f32_32x32x16_bf16 v[0:15], v[64:67], v[162:165], v[0:15]
	ds_read_b64_tr_b16 v[76:77], v140 offset:53248
	ds_read_b64_tr_b16 v[78:79], v141 offset:53248
	ds_read_b64_tr_b16 v[174:175], v142 offset:47104
	ds_read_b64_tr_b16 v[176:177], v142 offset:47616
	s_cmp_eq_u32 s96, 0
	s_cbranch_scc1 .Lgs5_nochain
	s_cmp_eq_u32 s76, 1
	s_cbranch_scc1 .Lgs5_nochain
	s_waitcnt lgkmcnt(8)
	v_mfma_f32_32x32x16_bf16 v[0:15], v[68:71], v[166:169], v[0:15]
	ds_read_b128 v[32:35], v220
	ds_read_b128 v[48:51], v221 offset:40960
	v_xor_b32_e32 v198, 32, v220
	v_xor_b32_e32 v199, 32, v221
	ds_read_b128 v[36:39], v198
	ds_read_b128 v[52:55], v199 offset:40960
	global_load_dwordx4 v[222:225], v134, s[6:7]
	s_waitcnt lgkmcnt(8)
	v_mfma_f32_32x32x16_bf16 v[0:15], v[72:75], v[170:173], v[0:15]
	v_xor_b32_e32 v198, 64, v220
	v_xor_b32_e32 v199, 64, v221
	ds_read_b128 v[40:43], v198
	ds_read_b128 v[56:59], v199 offset:40960
	v_xor_b32_e32 v198, 96, v220
	v_xor_b32_e32 v199, 96, v221
	ds_read_b128 v[44:47], v198
	ds_read_b128 v[60:63], v199 offset:40960
	global_load_dwordx4 v[226:229], v134, s[6:7] offset:128
	s_waitcnt lgkmcnt(8)
	v_mfma_f32_32x32x16_bf16 v[0:15], v[76:79], v[174:177], v[0:15]
	global_load_dwordx4 v[230:233], v134, s[8:9]
	s_waitcnt lgkmcnt(6)
	v_mfma_f32_32x32x16_bf16 v[146:161], v[32:35], v[48:51], 0
	v_xor_b32_e32 v198, 128, v220
	v_xor_b32_e32 v199, 128, v221
	ds_read_b128 v[32:35], v198
	ds_read_b128 v[48:51], v199 offset:40960
	global_load_dwordx4 v[234:237], v134, s[8:9] offset:128
	s_waitcnt lgkmcnt(6)
	v_mfma_f32_32x32x16_bf16 v[146:161], v[36:39], v[52:55], v[146:161]
	v_xor_b32_e32 v198, 160, v220
	v_xor_b32_e32 v199, 160, v221
	ds_read_b128 v[36:39], v198
	ds_read_b128 v[52:55], v199 offset:40960
	global_load_dwordx4 v[244:247], v135, s[10:11]
	s_waitcnt lgkmcnt(6)
	v_mfma_f32_32x32x16_bf16 v[146:161], v[40:43], v[56:59], v[146:161]
	v_xor_b32_e32 v198, 192, v220
	v_xor_b32_e32 v199, 192, v221
	ds_read_b128 v[40:43], v198
	ds_read_b128 v[56:59], v199 offset:40960
	global_load_dword v248, v145, s[18:19]
	s_waitcnt lgkmcnt(6)
	v_mfma_f32_32x32x16_bf16 v[146:161], v[44:47], v[60:63], v[146:161]
	v_xor_b32_e32 v198, 224, v220
	v_xor_b32_e32 v199, 224, v221
	ds_read_b128 v[44:47], v198
	ds_read_b128 v[60:63], v199 offset:40960
	s_waitcnt lgkmcnt(6)
	v_mfma_f32_32x32x16_bf16 v[146:161], v[32:35], v[48:51], v[146:161]
	ds_read_b128 v[178:181], v252 offset:512
	ds_read_b128 v[182:185], v252 offset:544
	ds_read_b128 v[186:189], v252 offset:576
	ds_read_b128 v[190:193], v252 offset:608
	s_waitcnt lgkmcnt(8)
	v_mfma_f32_32x32x16_bf16 v[146:161], v[36:39], v[52:55], v[146:161]
	s_waitcnt lgkmcnt(6)
	v_mfma_f32_32x32x16_bf16 v[146:161], v[40:43], v[56:59], v[146:161]
	s_waitcnt lgkmcnt(4)
	v_mfma_f32_32x32x16_bf16 v[146:161], v[44:47], v[60:63], v[146:161]
	s_cmp_eq_u32 s16, 0
	s_cbranch_scc1 .Lgs5_scale
	s_cmp_eq_u32 s76, 2
	s_cbranch_scc0 .Lgs5_scale
	v_xor_b32_e32 v198, 32, v249
	ds_read_b128 v[64:67], v249 offset:0
	ds_read_b128 v[68:71], v198 offset:0
	s_cmp_eq_u32 s77, 0
	s_cbranch_scc1 .Lgs5_ohalf
	v_xor_b32_e32 v199, 64, v249
	v_xor_b32_e32 v200, 96, v249
	ds_read_b128 v[72:75], v199 offset:0
	ds_read_b128 v[76:79], v200 offset:0
	s_waitcnt lgkmcnt(2)
	v_mfma_f32_32x32x16_bf16 v[16:31], v[80:83], v[64:67], v[16:31]
	v_mfma_f32_32x32x16_bf16 v[16:31], v[84:87], v[68:71], v[16:31]
	s_waitcnt lgkmcnt(0)
	v_mfma_f32_32x32x16_bf16 v[16:31], v[88:91], v[72:75], v[16:31]
	v_mfma_f32_32x32x16_bf16 v[16:31], v[92:95], v[76:79], v[16:31]
	s_branch .Lgs5_odone

; __device__ __forceinline__ u16 f2bf(float x) { return (u16)(cvtpk(x, 0.f) & 0xffffu); }
; __device__ __forceinline__ int crow(int r, int hi) { return (r & 3) + 8 * (r >> 2) + 4 * hi; }
; __device__ __forceinline__ void gla_scan_phase(const Params& p, int j, bool need_ctx, char* smem, int tid, int bid) {
;     ...
;         if (!is_ctx || need_ctx) {
;           u16* O = dir ? OB : OF;
; #pragma unroll
;           for (int r = 0; r < 16; ++r) {
;             const int pos = c * 64 + tbo * 32 + crow(r, hi);
;             const int tok = dir ? TT - 1 - pos : pos;
;             O[(size_t)(base + tok) * 1024 + h * 256 + dvs * 64 + dvbo * 32 + l32] = f2bf(oacc[r]);
;           }
;         }
.Lgs_t_odone:
	s_nop 7
	s_nop 7
	s_add_i32 s65, s54, -1
	s_cmp_lt_u32 s65, 4
	s_cselect_b32 s0, s35, s55
	s_mul_i32 s1, s65, s80
	s_add_u32 s0, s0, s1
	s_lshl_b32 s1, s0, 11
	s_add_u32 s20, s30, s1
	s_addc_u32 s21, s31, 0
	v_cvt_pk_bf16_f32 v186, v146, v147
	v_cvt_pk_bf16_f32 v187, v148, v149
	v_cvt_pk_bf16_f32 v188, v150, v151
	v_cvt_pk_bf16_f32 v189, v152, v153
	v_cvt_pk_bf16_f32 v190, v154, v155
	v_cvt_pk_bf16_f32 v191, v156, v157
	v_cvt_pk_bf16_f32 v192, v158, v159
	v_cvt_pk_bf16_f32 v193, v160, v161
	s_nop 0
	v_permlane32_swap_b32_e32 v186, v188
	v_permlane32_swap_b32_e32 v187, v189
	v_permlane32_swap_b32_e32 v190, v192
	v_permlane32_swap_b32_e32 v191, v193
	global_store_dwordx4 v204, v[186:189], s[20:21]
	global_store_dwordx4 v204, v[190:193], s[20:21] offset:32
